# speedup vs baseline: 1.0005x; 1.0005x over previous
; DI unsigned pack2(float a, float b) { return (unsigned)f2bf(a) | ((unsigned)f2bf(b) << 16); }
; DI float bflo(unsigned w) { return __uint_as_float(w << 16); }
; DI float bfhi(unsigned w) { return __uint_as_float(w & 0xffff0000u); }
;   DI void operator()(f32x4 (&acc)[4][4], int m0w, int n0w, int fr, int fq) const {
; #pragma unroll
;     for (int mi = 0; mi < 4; ++mi)
; #pragma unroll
;       for (int ni = 0; ni < 4; ++ni) {
;         const size_t o = (size_t)(m0w + mi * 16 + fr) * D + n0w + ni * 16 + fq * 4;
;         const uint2 gw = *(const uint2*)(G + o);
;         f32x4 m;
;         m[0] = bflo(gw.x) * acc[mi][ni][0]; m[1] = bfhi(gw.x) * acc[mi][ni][1];
;         m[2] = bflo(gw.y) * acc[mi][ni][2]; m[3] = bfhi(gw.y) * acc[mi][ni][3];
;         if (b > 0) m += *(const f32x4*)(MACC + o);
;         if (b < 2) *(f32x4*)(MACC + o) = m;
;         else { uint2 w; w.x = pack2(m[0], m[1]); w.y = pack2(m[2], m[3]); *(uint2*)(MERGED + o) = w; }
;       }
.LBB0_464:
	s_setprio 3
	v_add_u32_e32 v136, s2, v155
	v_or_b32_e32 v133, s3, v145
	v_readlane_b32 s0, v248, 7
	v_readlane_b32 s1, v248, 8
	v_ashrrev_i32_e32 v135, 31, v133
	v_or_b32_e32 v134, v133, v132
	v_readlane_b32 s40, v246, 1
	v_readlane_b32 s41, v246, 2
	v_readlane_b32 s42, v246, 3
	v_readlane_b32 s43, v246, 4
	v_readlane_b32 s44, v246, 5
	v_readlane_b32 s45, v246, 6
	v_readlane_b32 s46, v246, 7
	v_readlane_b32 s47, v246, 8
	v_readlane_b32 s2, v248, 3
	v_readlane_b32 s3, v248, 4
	s_nop 1
	s_sub_u32 s2, s2, s0
	s_subb_u32 s3, s3, s1
	v_mov_b32_e32 v138, v136
	v_ashrrev_i32_e32 v139, 31, v138
	v_lshlrev_b64 v[138:139], 11, v[138:139]
	v_lshl_add_u64 v[138:139], v[138:139], 0, v[134:135]
	v_lshl_add_u64 v[140:141], v[138:139], 1, s[0:1]
	v_lshl_add_u64 v[150:151], v[138:139], 2, s[42:43]
	global_load_dwordx2 v[156:157], v[140:141], off
	global_load_dwordx2 v[158:159], v[140:141], off offset:32
	global_load_dwordx2 v[160:161], v[140:141], off offset:64
	global_load_dwordx2 v[162:163], v[140:141], off offset:96
	v_or_b32_e32 v138, 16, v136
	v_ashrrev_i32_e32 v139, 31, v138
	v_lshlrev_b64 v[138:139], 11, v[138:139]
	v_lshl_add_u64 v[138:139], v[138:139], 0, v[134:135]
	v_lshl_add_u64 v[142:143], v[138:139], 1, s[0:1]
	v_lshl_add_u64 v[152:153], v[138:139], 2, s[42:43]
	global_load_dwordx2 v[164:165], v[142:143], off
	global_load_dwordx2 v[166:167], v[142:143], off offset:32
	global_load_dwordx2 v[168:169], v[142:143], off offset:64
	global_load_dwordx2 v[170:171], v[142:143], off offset:96
	v_or_b32_e32 v138, 32, v136
	v_ashrrev_i32_e32 v139, 31, v138
	v_lshlrev_b64 v[138:139], 11, v[138:139]
	v_lshl_add_u64 v[138:139], v[138:139], 0, v[134:135]
	v_lshl_add_u64 v[146:147], v[138:139], 1, s[0:1]
	v_lshl_add_u64 v[236:237], v[138:139], 2, s[42:43]
	global_load_dwordx2 v[172:173], v[146:147], off
	global_load_dwordx2 v[174:175], v[146:147], off offset:32
	global_load_dwordx2 v[176:177], v[146:147], off offset:64
	global_load_dwordx2 v[178:179], v[146:147], off offset:96
	v_or_b32_e32 v138, 48, v136
	v_ashrrev_i32_e32 v139, 31, v138
	v_lshlrev_b64 v[138:139], 11, v[138:139]
	v_lshl_add_u64 v[138:139], v[138:139], 0, v[134:135]
	v_lshl_add_u64 v[148:149], v[138:139], 1, s[0:1]
	v_lshl_add_u64 v[238:239], v[138:139], 2, s[42:43]
	global_load_dwordx2 v[180:181], v[148:149], off
	global_load_dwordx2 v[182:183], v[148:149], off offset:32
	global_load_dwordx2 v[226:227], v[148:149], off offset:64
	global_load_dwordx2 v[228:229], v[148:149], off offset:96
	s_and_b64 vcc, exec, s[22:23]
	s_cbranch_vccz .Lem_n
	s_and_b64 vcc, exec, s[24:25]
	s_cbranch_vccz .Lem_lp
	global_load_dwordx4 v[186:189], v[150:151], off
	global_load_dwordx4 v[190:193], v[150:151], off offset:64
	global_load_dwordx4 v[194:197], v[150:151], off offset:128
	global_load_dwordx4 v[198:201], v[150:151], off offset:192
	global_load_dwordx4 v[202:205], v[152:153], off
	global_load_dwordx4 v[206:209], v[152:153], off offset:64
	global_load_dwordx4 v[210:213], v[152:153], off offset:128
	global_load_dwordx4 v[230:233], v[152:153], off offset:192
	s_waitcnt vmcnt(7)
	v_lshlrev_b32_e32 v244, 16, v156
	v_and_b32_e32 v245, 0xffff0000, v156
	v_lshlrev_b32_e32 v156, 16, v157
	v_and_b32_e32 v157, 0xffff0000, v157
	v_pk_mul_f32 v[126:127], v[126:127], v[156:157]
	v_pk_mul_f32 v[124:125], v[124:125], v[244:245]
	v_pk_add_f32 v[126:127], v[126:127], v[188:189]
	v_pk_add_f32 v[124:125], v[124:125], v[186:187]
	global_store_dwordx4 v[150:151], v[124:127], off
	global_load_dwordx4 v[186:189], v[236:237], off
	s_waitcnt vmcnt(8)
	v_lshlrev_b32_e32 v244, 16, v158
	v_and_b32_e32 v245, 0xffff0000, v158
	v_lshlrev_b32_e32 v158, 16, v159
	v_and_b32_e32 v159, 0xffff0000, v159
	v_pk_mul_f32 v[122:123], v[122:123], v[158:159]
	v_pk_mul_f32 v[120:121], v[120:121], v[244:245]
	v_pk_add_f32 v[122:123], v[122:123], v[192:193]
	v_pk_add_f32 v[120:121], v[120:121], v[190:191]
	global_store_dwordx4 v[150:151], v[120:123], off offset:64
	global_load_dwordx4 v[190:193], v[236:237], off offset:64
	s_waitcnt vmcnt(9)
	v_lshlrev_b32_e32 v244, 16, v160
	v_and_b32_e32 v245, 0xffff0000, v160
	v_lshlrev_b32_e32 v160, 16, v161
	v_and_b32_e32 v161, 0xffff0000, v161
	v_pk_mul_f32 v[118:119], v[118:119], v[160:161]
	v_pk_mul_f32 v[116:117], v[116:117], v[244:245]
	v_pk_add_f32 v[118:119], v[118:119], v[196:197]
	v_pk_add_f32 v[116:117], v[116:117], v[194:195]
	global_store_dwordx4 v[150:151], v[116:119], off offset:128
	global_load_dwordx4 v[194:197], v[236:237], off offset:128
	s_waitcnt vmcnt(10)
	v_lshlrev_b32_e32 v244, 16, v162
	v_and_b32_e32 v245, 0xffff0000, v162
	v_lshlrev_b32_e32 v162, 16, v163
	v_and_b32_e32 v163, 0xffff0000, v163
	v_pk_mul_f32 v[114:115], v[114:115], v[162:163]
	v_pk_mul_f32 v[112:113], v[112:113], v[244:245]
	v_pk_add_f32 v[114:115], v[114:115], v[200:201]
	v_pk_add_f32 v[112:113], v[112:113], v[198:199]
	global_store_dwordx4 v[150:151], v[112:115], off offset:192
	global_load_dwordx4 v[198:201], v[236:237], off offset:192
	s_waitcnt vmcnt(11)
	v_lshlrev_b32_e32 v244, 16, v164
	v_and_b32_e32 v245, 0xffff0000, v164
	v_lshlrev_b32_e32 v164, 16, v165
	v_and_b32_e32 v165, 0xffff0000, v165
	v_pk_mul_f32 v[110:111], v[110:111], v[164:165]
	v_pk_mul_f32 v[108:109], v[108:109], v[244:245]
	v_pk_add_f32 v[110:111], v[110:111], v[204:205]
	v_pk_add_f32 v[108:109], v[108:109], v[202:203]
	global_store_dwordx4 v[152:153], v[108:111], off
	global_load_dwordx4 v[202:205], v[238:239], off
	s_waitcnt vmcnt(12)
; DI float bflo(unsigned w) { return __uint_as_float(w << 16); }
; DI float bfhi(unsigned w) { return __uint_as_float(w & 0xffff0000u); }
;   DI void operator()(f32x4 (&acc)[4][4], int m0w, int n0w, int fr, int fq) const {
;     ...
;         const size_t o = (size_t)(m0w + mi * 16 + fr) * D + n0w + ni * 16 + fq * 4;
;         const uint2 gw = *(const uint2*)(G + o);
;         f32x4 m;
;         m[0] = bflo(gw.x) * acc[mi][ni][0]; m[1] = bfhi(gw.x) * acc[mi][ni][1];
;         m[2] = bflo(gw.y) * acc[mi][ni][2]; m[3] = bfhi(gw.y) * acc[mi][ni][3];
;         if (b > 0) m += *(const f32x4*)(MACC + o);
;         if (b < 2) *(f32x4*)(MACC + o) = m;
	v_lshlrev_b32_e32 v244, 16, v166
	v_and_b32_e32 v245, 0xffff0000, v166
	v_lshlrev_b32_e32 v166, 16, v167
	v_and_b32_e32 v167, 0xffff0000, v167
	v_pk_mul_f32 v[106:107], v[106:107], v[166:167]
	v_pk_mul_f32 v[104:105], v[104:105], v[244:245]
	v_pk_add_f32 v[106:107], v[106:107], v[208:209]
	v_pk_add_f32 v[104:105], v[104:105], v[206:207]
	global_store_dwordx4 v[152:153], v[104:107], off offset:64
	global_load_dwordx4 v[206:209], v[238:239], off offset:64
	s_waitcnt vmcnt(13)
	v_lshlrev_b32_e32 v244, 16, v168
	v_and_b32_e32 v245, 0xffff0000, v168
	v_lshlrev_b32_e32 v168, 16, v169
	v_and_b32_e32 v169, 0xffff0000, v169
	v_pk_mul_f32 v[102:103], v[102:103], v[168:169]
	v_pk_mul_f32 v[100:101], v[100:101], v[244:245]
	v_pk_add_f32 v[102:103], v[102:103], v[212:213]
	v_pk_add_f32 v[100:101], v[100:101], v[210:211]
	global_store_dwordx4 v[152:153], v[100:103], off offset:128
	global_load_dwordx4 v[210:213], v[238:239], off offset:128
	s_waitcnt vmcnt(14)
	v_lshlrev_b32_e32 v244, 16, v170
	v_and_b32_e32 v245, 0xffff0000, v170
	v_lshlrev_b32_e32 v170, 16, v171
	v_and_b32_e32 v171, 0xffff0000, v171
	v_pk_mul_f32 v[98:99], v[98:99], v[170:171]
	v_pk_mul_f32 v[96:97], v[96:97], v[244:245]
	v_pk_add_f32 v[98:99], v[98:99], v[232:233]
	v_pk_add_f32 v[96:97], v[96:97], v[230:231]
	global_store_dwordx4 v[152:153], v[96:99], off offset:192
	global_load_dwordx4 v[230:233], v[238:239], off offset:192
	s_waitcnt vmcnt(14)
	v_lshlrev_b32_e32 v244, 16, v172
	v_and_b32_e32 v245, 0xffff0000, v172
	v_lshlrev_b32_e32 v172, 16, v173
	v_and_b32_e32 v173, 0xffff0000, v173
	v_pk_mul_f32 v[94:95], v[94:95], v[172:173]
	v_pk_mul_f32 v[92:93], v[92:93], v[244:245]
	v_pk_add_f32 v[94:95], v[94:95], v[188:189]
	v_pk_add_f32 v[92:93], v[92:93], v[186:187]
	global_store_dwordx4 v[236:237], v[92:95], off
	s_waitcnt vmcnt(13)
	v_lshlrev_b32_e32 v244, 16, v174
	v_and_b32_e32 v245, 0xffff0000, v174
	v_lshlrev_b32_e32 v174, 16, v175
	v_and_b32_e32 v175, 0xffff0000, v175
	v_pk_mul_f32 v[90:91], v[90:91], v[174:175]
	v_pk_mul_f32 v[88:89], v[88:89], v[244:245]
	v_pk_add_f32 v[90:91], v[90:91], v[192:193]
	v_pk_add_f32 v[88:89], v[88:89], v[190:191]
	global_store_dwordx4 v[236:237], v[88:91], off offset:64
	s_waitcnt vmcnt(12)
	v_lshlrev_b32_e32 v244, 16, v176
	v_and_b32_e32 v245, 0xffff0000, v176
	v_lshlrev_b32_e32 v176, 16, v177
	v_and_b32_e32 v177, 0xffff0000, v177
	v_pk_mul_f32 v[86:87], v[86:87], v[176:177]
	v_pk_mul_f32 v[84:85], v[84:85], v[244:245]
	v_pk_add_f32 v[86:87], v[86:87], v[196:197]
	v_pk_add_f32 v[84:85], v[84:85], v[194:195]
	global_store_dwordx4 v[236:237], v[84:87], off offset:128
	s_waitcnt vmcnt(11)
	v_lshlrev_b32_e32 v244, 16, v178
	v_and_b32_e32 v245, 0xffff0000, v178
	v_lshlrev_b32_e32 v178, 16, v179
	v_and_b32_e32 v179, 0xffff0000, v179
	v_pk_mul_f32 v[82:83], v[82:83], v[178:179]
	v_pk_mul_f32 v[80:81], v[80:81], v[244:245]
	v_pk_add_f32 v[82:83], v[82:83], v[200:201]
	v_pk_add_f32 v[80:81], v[80:81], v[198:199]
	global_store_dwordx4 v[236:237], v[80:83], off offset:192
	s_waitcnt vmcnt(10)
	v_lshlrev_b32_e32 v244, 16, v180
	v_and_b32_e32 v245, 0xffff0000, v180
	v_lshlrev_b32_e32 v180, 16, v181
	v_and_b32_e32 v181, 0xffff0000, v181
	v_pk_mul_f32 v[78:79], v[78:79], v[180:181]
	v_pk_mul_f32 v[76:77], v[76:77], v[244:245]
	v_pk_add_f32 v[78:79], v[78:79], v[204:205]
	v_pk_add_f32 v[76:77], v[76:77], v[202:203]
	global_store_dwordx4 v[238:239], v[76:79], off
	s_waitcnt vmcnt(9)
	v_lshlrev_b32_e32 v244, 16, v182
	v_and_b32_e32 v245, 0xffff0000, v182
	v_lshlrev_b32_e32 v182, 16, v183
	v_and_b32_e32 v183, 0xffff0000, v183
	v_pk_mul_f32 v[74:75], v[74:75], v[182:183]
	v_pk_mul_f32 v[72:73], v[72:73], v[244:245]
	v_pk_add_f32 v[74:75], v[74:75], v[208:209]
	v_pk_add_f32 v[72:73], v[72:73], v[206:207]
	global_store_dwordx4 v[238:239], v[72:75], off offset:64
	s_waitcnt vmcnt(8)
	v_lshlrev_b32_e32 v244, 16, v226
	v_and_b32_e32 v245, 0xffff0000, v226
	v_lshlrev_b32_e32 v226, 16, v227
	v_and_b32_e32 v227, 0xffff0000, v227
	v_pk_mul_f32 v[70:71], v[70:71], v[226:227]
	v_pk_mul_f32 v[68:69], v[68:69], v[244:245]
	v_pk_add_f32 v[70:71], v[70:71], v[212:213]
	v_pk_add_f32 v[68:69], v[68:69], v[210:211]
	global_store_dwordx4 v[238:239], v[68:71], off offset:128
	s_waitcnt vmcnt(7)
	v_lshlrev_b32_e32 v244, 16, v228
	v_and_b32_e32 v245, 0xffff0000, v228
	v_lshlrev_b32_e32 v228, 16, v229
	v_and_b32_e32 v229, 0xffff0000, v229
	v_pk_mul_f32 v[66:67], v[66:67], v[228:229]
	v_pk_mul_f32 v[64:65], v[64:65], v[244:245]
	v_pk_add_f32 v[66:67], v[66:67], v[232:233]
	v_pk_add_f32 v[64:65], v[64:65], v[230:231]
	global_store_dwordx4 v[238:239], v[64:67], off offset:192
	s_setprio 0
	s_branch .LBB0_450
; DI unsigned pack2(float a, float b) { return (unsigned)f2bf(a) | ((unsigned)f2bf(b) << 16); }
; DI float bflo(unsigned w) { return __uint_as_float(w << 16); }
; DI float bfhi(unsigned w) { return __uint_as_float(w & 0xffff0000u); }
;   DI void operator()(f32x4 (&acc)[4][4], int m0w, int n0w, int fr, int fq) const {
;     ...
;         const size_t o = (size_t)(m0w + mi * 16 + fr) * D + n0w + ni * 16 + fq * 4;
;         const uint2 gw = *(const uint2*)(G + o);
;         f32x4 m;
;         m[0] = bflo(gw.x) * acc[mi][ni][0]; m[1] = bfhi(gw.x) * acc[mi][ni][1];
;         m[2] = bflo(gw.y) * acc[mi][ni][2]; m[3] = bfhi(gw.y) * acc[mi][ni][3];
;         if (b > 0) m += *(const f32x4*)(MACC + o);
;         if (b < 2) *(f32x4*)(MACC + o) = m;
;         else { uint2 w; w.x = pack2(m[0], m[1]); w.y = pack2(m[2], m[3]); *(uint2*)(MERGED + o) = w; }
.Lem_lp:
	global_load_dwordx4 v[186:189], v[150:151], off
	global_load_dwordx4 v[190:193], v[150:151], off offset:64
	global_load_dwordx4 v[194:197], v[150:151], off offset:128
	global_load_dwordx4 v[198:201], v[150:151], off offset:192
	global_load_dwordx4 v[202:205], v[152:153], off
	global_load_dwordx4 v[206:209], v[152:153], off offset:64
	global_load_dwordx4 v[210:213], v[152:153], off offset:128
	global_load_dwordx4 v[230:233], v[152:153], off offset:192
	s_waitcnt vmcnt(7)
	v_lshlrev_b32_e32 v244, 16, v156
	v_and_b32_e32 v245, 0xffff0000, v156
	v_lshlrev_b32_e32 v156, 16, v157
	v_and_b32_e32 v157, 0xffff0000, v157
	v_pk_mul_f32 v[126:127], v[126:127], v[156:157]
	v_pk_mul_f32 v[124:125], v[124:125], v[244:245]
	v_pk_add_f32 v[126:127], v[126:127], v[188:189]
	v_pk_add_f32 v[124:125], v[124:125], v[186:187]
	v_lshl_add_u64 v[240:241], v[140:141], 0, s[2:3]
	v_cvt_pk_bf16_f32 v124, v124, v125
	v_cvt_pk_bf16_f32 v125, v126, v127
	global_store_dwordx2 v[240:241], v[124:125], off
	global_load_dwordx4 v[186:189], v[236:237], off
	s_waitcnt vmcnt(8)
	v_lshlrev_b32_e32 v244, 16, v158
	v_and_b32_e32 v245, 0xffff0000, v158
	v_lshlrev_b32_e32 v158, 16, v159
	v_and_b32_e32 v159, 0xffff0000, v159
	v_pk_mul_f32 v[122:123], v[122:123], v[158:159]
	v_pk_mul_f32 v[120:121], v[120:121], v[244:245]
	v_pk_add_f32 v[122:123], v[122:123], v[192:193]
	v_pk_add_f32 v[120:121], v[120:121], v[190:191]
	v_cvt_pk_bf16_f32 v120, v120, v121
	v_cvt_pk_bf16_f32 v121, v122, v123
	global_store_dwordx2 v[240:241], v[120:121], off offset:32
	global_load_dwordx4 v[190:193], v[236:237], off offset:64
	s_waitcnt vmcnt(9)
	v_lshlrev_b32_e32 v244, 16, v160
	v_and_b32_e32 v245, 0xffff0000, v160
	v_lshlrev_b32_e32 v160, 16, v161
	v_and_b32_e32 v161, 0xffff0000, v161
	v_pk_mul_f32 v[118:119], v[118:119], v[160:161]
	v_pk_mul_f32 v[116:117], v[116:117], v[244:245]
	v_pk_add_f32 v[118:119], v[118:119], v[196:197]
	v_pk_add_f32 v[116:117], v[116:117], v[194:195]
	v_cvt_pk_bf16_f32 v116, v116, v117
	v_cvt_pk_bf16_f32 v117, v118, v119
	global_store_dwordx2 v[240:241], v[116:117], off offset:64
	global_load_dwordx4 v[194:197], v[236:237], off offset:128
	s_waitcnt vmcnt(10)
	v_lshlrev_b32_e32 v244, 16, v162
	v_and_b32_e32 v245, 0xffff0000, v162
	v_lshlrev_b32_e32 v162, 16, v163
	v_and_b32_e32 v163, 0xffff0000, v163
	v_pk_mul_f32 v[114:115], v[114:115], v[162:163]
	v_pk_mul_f32 v[112:113], v[112:113], v[244:245]
	v_pk_add_f32 v[114:115], v[114:115], v[200:201]
	v_pk_add_f32 v[112:113], v[112:113], v[198:199]
	v_cvt_pk_bf16_f32 v112, v112, v113
	v_cvt_pk_bf16_f32 v113, v114, v115
	global_store_dwordx2 v[240:241], v[112:113], off offset:96
	global_load_dwordx4 v[198:201], v[236:237], off offset:192
	s_waitcnt vmcnt(11)
	v_lshlrev_b32_e32 v244, 16, v164
	v_and_b32_e32 v245, 0xffff0000, v164
	v_lshlrev_b32_e32 v164, 16, v165
	v_and_b32_e32 v165, 0xffff0000, v165
	v_pk_mul_f32 v[110:111], v[110:111], v[164:165]
	v_pk_mul_f32 v[108:109], v[108:109], v[244:245]
	v_pk_add_f32 v[110:111], v[110:111], v[204:205]
	v_pk_add_f32 v[108:109], v[108:109], v[202:203]
	v_lshl_add_u64 v[242:243], v[142:143], 0, s[2:3]
	v_cvt_pk_bf16_f32 v108, v108, v109
	v_cvt_pk_bf16_f32 v109, v110, v111
	global_store_dwordx2 v[242:243], v[108:109], off
	global_load_dwordx4 v[202:205], v[238:239], off
	s_waitcnt vmcnt(12)
	v_lshlrev_b32_e32 v244, 16, v166
	v_and_b32_e32 v245, 0xffff0000, v166
	v_lshlrev_b32_e32 v166, 16, v167
	v_and_b32_e32 v167, 0xffff0000, v167
	v_pk_mul_f32 v[106:107], v[106:107], v[166:167]
	v_pk_mul_f32 v[104:105], v[104:105], v[244:245]
	v_pk_add_f32 v[106:107], v[106:107], v[208:209]
	v_pk_add_f32 v[104:105], v[104:105], v[206:207]
	v_cvt_pk_bf16_f32 v104, v104, v105
	v_cvt_pk_bf16_f32 v105, v106, v107
	global_store_dwordx2 v[242:243], v[104:105], off offset:32
	global_load_dwordx4 v[206:209], v[238:239], off offset:64
	s_waitcnt vmcnt(13)
	v_lshlrev_b32_e32 v244, 16, v168
	v_and_b32_e32 v245, 0xffff0000, v168
	v_lshlrev_b32_e32 v168, 16, v169
	v_and_b32_e32 v169, 0xffff0000, v169
	v_pk_mul_f32 v[102:103], v[102:103], v[168:169]
	v_pk_mul_f32 v[100:101], v[100:101], v[244:245]
	v_pk_add_f32 v[102:103], v[102:103], v[212:213]
	v_pk_add_f32 v[100:101], v[100:101], v[210:211]
	v_cvt_pk_bf16_f32 v100, v100, v101
	v_cvt_pk_bf16_f32 v101, v102, v103
	global_store_dwordx2 v[242:243], v[100:101], off offset:64
	global_load_dwordx4 v[210:213], v[238:239], off offset:128
	s_waitcnt vmcnt(14)
	v_lshlrev_b32_e32 v244, 16, v170
	v_and_b32_e32 v245, 0xffff0000, v170
	v_lshlrev_b32_e32 v170, 16, v171
	v_and_b32_e32 v171, 0xffff0000, v171
	v_pk_mul_f32 v[98:99], v[98:99], v[170:171]
	v_pk_mul_f32 v[96:97], v[96:97], v[244:245]
	v_pk_add_f32 v[98:99], v[98:99], v[232:233]
	v_pk_add_f32 v[96:97], v[96:97], v[230:231]
	v_cvt_pk_bf16_f32 v96, v96, v97
	v_cvt_pk_bf16_f32 v97, v98, v99
	global_store_dwordx2 v[242:243], v[96:97], off offset:96
	global_load_dwordx4 v[230:233], v[238:239], off offset:192
	s_waitcnt vmcnt(14)
	v_lshlrev_b32_e32 v244, 16, v172
	v_and_b32_e32 v245, 0xffff0000, v172
	v_lshlrev_b32_e32 v172, 16, v173
	v_and_b32_e32 v173, 0xffff0000, v173
	v_pk_mul_f32 v[94:95], v[94:95], v[172:173]
	v_pk_mul_f32 v[92:93], v[92:93], v[244:245]
	v_pk_add_f32 v[94:95], v[94:95], v[188:189]
	v_pk_add_f32 v[92:93], v[92:93], v[186:187]
	v_lshl_add_u64 v[240:241], v[146:147], 0, s[2:3]
	v_cvt_pk_bf16_f32 v92, v92, v93
	v_cvt_pk_bf16_f32 v93, v94, v95
	global_store_dwordx2 v[240:241], v[92:93], off
	s_waitcnt vmcnt(13)
; DI unsigned pack2(float a, float b) { return (unsigned)f2bf(a) | ((unsigned)f2bf(b) << 16); }
; DI float bflo(unsigned w) { return __uint_as_float(w << 16); }
; DI float bfhi(unsigned w) { return __uint_as_float(w & 0xffff0000u); }
;   DI void operator()(f32x4 (&acc)[4][4], int m0w, int n0w, int fr, int fq) const {
;     ...
;         const size_t o = (size_t)(m0w + mi * 16 + fr) * D + n0w + ni * 16 + fq * 4;
;         const uint2 gw = *(const uint2*)(G + o);
;         f32x4 m;
;         m[0] = bflo(gw.x) * acc[mi][ni][0]; m[1] = bfhi(gw.x) * acc[mi][ni][1];
;         m[2] = bflo(gw.y) * acc[mi][ni][2]; m[3] = bfhi(gw.y) * acc[mi][ni][3];
;         if (b > 0) m += *(const f32x4*)(MACC + o);
;         if (b < 2) *(f32x4*)(MACC + o) = m;
;         else { uint2 w; w.x = pack2(m[0], m[1]); w.y = pack2(m[2], m[3]); *(uint2*)(MERGED + o) = w; }
	v_lshlrev_b32_e32 v244, 16, v174
	v_and_b32_e32 v245, 0xffff0000, v174
	v_lshlrev_b32_e32 v174, 16, v175
	v_and_b32_e32 v175, 0xffff0000, v175
	v_pk_mul_f32 v[90:91], v[90:91], v[174:175]
	v_pk_mul_f32 v[88:89], v[88:89], v[244:245]
	v_pk_add_f32 v[90:91], v[90:91], v[192:193]
	v_pk_add_f32 v[88:89], v[88:89], v[190:191]
	v_cvt_pk_bf16_f32 v88, v88, v89
	v_cvt_pk_bf16_f32 v89, v90, v91
	global_store_dwordx2 v[240:241], v[88:89], off offset:32
	s_waitcnt vmcnt(12)
	v_lshlrev_b32_e32 v244, 16, v176
	v_and_b32_e32 v245, 0xffff0000, v176
	v_lshlrev_b32_e32 v176, 16, v177
	v_and_b32_e32 v177, 0xffff0000, v177
	v_pk_mul_f32 v[86:87], v[86:87], v[176:177]
	v_pk_mul_f32 v[84:85], v[84:85], v[244:245]
	v_pk_add_f32 v[86:87], v[86:87], v[196:197]
	v_pk_add_f32 v[84:85], v[84:85], v[194:195]
	v_cvt_pk_bf16_f32 v84, v84, v85
	v_cvt_pk_bf16_f32 v85, v86, v87
	global_store_dwordx2 v[240:241], v[84:85], off offset:64
	s_waitcnt vmcnt(11)
	v_lshlrev_b32_e32 v244, 16, v178
	v_and_b32_e32 v245, 0xffff0000, v178
	v_lshlrev_b32_e32 v178, 16, v179
	v_and_b32_e32 v179, 0xffff0000, v179
	v_pk_mul_f32 v[82:83], v[82:83], v[178:179]
	v_pk_mul_f32 v[80:81], v[80:81], v[244:245]
	v_pk_add_f32 v[82:83], v[82:83], v[200:201]
	v_pk_add_f32 v[80:81], v[80:81], v[198:199]
	v_cvt_pk_bf16_f32 v80, v80, v81
	v_cvt_pk_bf16_f32 v81, v82, v83
	global_store_dwordx2 v[240:241], v[80:81], off offset:96
	s_waitcnt vmcnt(10)
	v_lshlrev_b32_e32 v244, 16, v180
	v_and_b32_e32 v245, 0xffff0000, v180
	v_lshlrev_b32_e32 v180, 16, v181
	v_and_b32_e32 v181, 0xffff0000, v181
	v_pk_mul_f32 v[78:79], v[78:79], v[180:181]
	v_pk_mul_f32 v[76:77], v[76:77], v[244:245]
	v_pk_add_f32 v[78:79], v[78:79], v[204:205]
	v_pk_add_f32 v[76:77], v[76:77], v[202:203]
	v_lshl_add_u64 v[242:243], v[148:149], 0, s[2:3]
	v_cvt_pk_bf16_f32 v76, v76, v77
	v_cvt_pk_bf16_f32 v77, v78, v79
	global_store_dwordx2 v[242:243], v[76:77], off
	s_waitcnt vmcnt(9)
	v_lshlrev_b32_e32 v244, 16, v182
	v_and_b32_e32 v245, 0xffff0000, v182
	v_lshlrev_b32_e32 v182, 16, v183
	v_and_b32_e32 v183, 0xffff0000, v183
	v_pk_mul_f32 v[74:75], v[74:75], v[182:183]
	v_pk_mul_f32 v[72:73], v[72:73], v[244:245]
	v_pk_add_f32 v[74:75], v[74:75], v[208:209]
	v_pk_add_f32 v[72:73], v[72:73], v[206:207]
	v_cvt_pk_bf16_f32 v72, v72, v73
	v_cvt_pk_bf16_f32 v73, v74, v75
	global_store_dwordx2 v[242:243], v[72:73], off offset:32
	s_waitcnt vmcnt(8)
	v_lshlrev_b32_e32 v244, 16, v226
	v_and_b32_e32 v245, 0xffff0000, v226
	v_lshlrev_b32_e32 v226, 16, v227
	v_and_b32_e32 v227, 0xffff0000, v227
	v_pk_mul_f32 v[70:71], v[70:71], v[226:227]
	v_pk_mul_f32 v[68:69], v[68:69], v[244:245]
	v_pk_add_f32 v[70:71], v[70:71], v[212:213]
	v_pk_add_f32 v[68:69], v[68:69], v[210:211]
	v_cvt_pk_bf16_f32 v68, v68, v69
	v_cvt_pk_bf16_f32 v69, v70, v71
	global_store_dwordx2 v[242:243], v[68:69], off offset:64
	s_waitcnt vmcnt(7)
	v_lshlrev_b32_e32 v244, 16, v228
	v_and_b32_e32 v245, 0xffff0000, v228
	v_lshlrev_b32_e32 v228, 16, v229
	v_and_b32_e32 v229, 0xffff0000, v229
	v_pk_mul_f32 v[66:67], v[66:67], v[228:229]
	v_pk_mul_f32 v[64:65], v[64:65], v[244:245]
	v_pk_add_f32 v[66:67], v[66:67], v[232:233]
	v_pk_add_f32 v[64:65], v[64:65], v[230:231]
	v_cvt_pk_bf16_f32 v64, v64, v65
	v_cvt_pk_bf16_f32 v65, v66, v67
	global_store_dwordx2 v[242:243], v[64:65], off offset:96
	s_setprio 0
	s_branch .LBB0_450
.Lem_n:
	s_and_b64 vcc, exec, s[24:25]
	s_cbranch_vccz .Lem_np
	s_waitcnt vmcnt(15)
	v_lshlrev_b32_e32 v244, 16, v156
	v_and_b32_e32 v245, 0xffff0000, v156
	v_lshlrev_b32_e32 v156, 16, v157
	v_and_b32_e32 v157, 0xffff0000, v157
	v_pk_mul_f32 v[126:127], v[126:127], v[156:157]
	v_pk_mul_f32 v[124:125], v[124:125], v[244:245]
	global_store_dwordx4 v[150:151], v[124:127], off
	s_waitcnt vmcnt(15)
	v_lshlrev_b32_e32 v244, 16, v158
	v_and_b32_e32 v245, 0xffff0000, v158
	v_lshlrev_b32_e32 v158, 16, v159
	v_and_b32_e32 v159, 0xffff0000, v159
	v_pk_mul_f32 v[122:123], v[122:123], v[158:159]
	v_pk_mul_f32 v[120:121], v[120:121], v[244:245]
	global_store_dwordx4 v[150:151], v[120:123], off offset:64
	s_waitcnt vmcnt(15)
	v_lshlrev_b32_e32 v244, 16, v160
	v_and_b32_e32 v245, 0xffff0000, v160
	v_lshlrev_b32_e32 v160, 16, v161
	v_and_b32_e32 v161, 0xffff0000, v161
	v_pk_mul_f32 v[118:119], v[118:119], v[160:161]
	v_pk_mul_f32 v[116:117], v[116:117], v[244:245]
	global_store_dwordx4 v[150:151], v[116:119], off offset:128
	s_waitcnt vmcnt(15)
	v_lshlrev_b32_e32 v244, 16, v162
	v_and_b32_e32 v245, 0xffff0000, v162
	v_lshlrev_b32_e32 v162, 16, v163
	v_and_b32_e32 v163, 0xffff0000, v163
	v_pk_mul_f32 v[114:115], v[114:115], v[162:163]
	v_pk_mul_f32 v[112:113], v[112:113], v[244:245]
	global_store_dwordx4 v[150:151], v[112:115], off offset:192
	s_waitcnt vmcnt(15)
	v_lshlrev_b32_e32 v244, 16, v164
	v_and_b32_e32 v245, 0xffff0000, v164
	v_lshlrev_b32_e32 v164, 16, v165
	v_and_b32_e32 v165, 0xffff0000, v165
	v_pk_mul_f32 v[110:111], v[110:111], v[164:165]
	v_pk_mul_f32 v[108:109], v[108:109], v[244:245]
	global_store_dwordx4 v[152:153], v[108:111], off
	s_waitcnt vmcnt(15)
	v_lshlrev_b32_e32 v244, 16, v166
	v_and_b32_e32 v245, 0xffff0000, v166
	v_lshlrev_b32_e32 v166, 16, v167
	v_and_b32_e32 v167, 0xffff0000, v167
	v_pk_mul_f32 v[106:107], v[106:107], v[166:167]
	v_pk_mul_f32 v[104:105], v[104:105], v[244:245]
	global_store_dwordx4 v[152:153], v[104:107], off offset:64
	s_waitcnt vmcnt(15)
	v_lshlrev_b32_e32 v244, 16, v168
	v_and_b32_e32 v245, 0xffff0000, v168
	v_lshlrev_b32_e32 v168, 16, v169
	v_and_b32_e32 v169, 0xffff0000, v169
	v_pk_mul_f32 v[102:103], v[102:103], v[168:169]
	v_pk_mul_f32 v[100:101], v[100:101], v[244:245]
	global_store_dwordx4 v[152:153], v[100:103], off offset:128
	s_waitcnt vmcnt(15)
; DI float bflo(unsigned w) { return __uint_as_float(w << 16); }
; DI float bfhi(unsigned w) { return __uint_as_float(w & 0xffff0000u); }
;   DI void operator()(f32x4 (&acc)[4][4], int m0w, int n0w, int fr, int fq) const {
;     ...
;         const size_t o = (size_t)(m0w + mi * 16 + fr) * D + n0w + ni * 16 + fq * 4;
;         const uint2 gw = *(const uint2*)(G + o);
;         f32x4 m;
;         m[0] = bflo(gw.x) * acc[mi][ni][0]; m[1] = bfhi(gw.x) * acc[mi][ni][1];
;         m[2] = bflo(gw.y) * acc[mi][ni][2]; m[3] = bfhi(gw.y) * acc[mi][ni][3];
;         if (b > 0) m += *(const f32x4*)(MACC + o);
;         if (b < 2) *(f32x4*)(MACC + o) = m;
	v_lshlrev_b32_e32 v244, 16, v170
	v_and_b32_e32 v245, 0xffff0000, v170
	v_lshlrev_b32_e32 v170, 16, v171
	v_and_b32_e32 v171, 0xffff0000, v171
	v_pk_mul_f32 v[98:99], v[98:99], v[170:171]
	v_pk_mul_f32 v[96:97], v[96:97], v[244:245]
	global_store_dwordx4 v[152:153], v[96:99], off offset:192
	s_waitcnt vmcnt(15)
	v_lshlrev_b32_e32 v244, 16, v172
	v_and_b32_e32 v245, 0xffff0000, v172
	v_lshlrev_b32_e32 v172, 16, v173
	v_and_b32_e32 v173, 0xffff0000, v173
	v_pk_mul_f32 v[94:95], v[94:95], v[172:173]
	v_pk_mul_f32 v[92:93], v[92:93], v[244:245]
	global_store_dwordx4 v[236:237], v[92:95], off
	s_waitcnt vmcnt(15)
	v_lshlrev_b32_e32 v244, 16, v174
	v_and_b32_e32 v245, 0xffff0000, v174
	v_lshlrev_b32_e32 v174, 16, v175
	v_and_b32_e32 v175, 0xffff0000, v175
	v_pk_mul_f32 v[90:91], v[90:91], v[174:175]
	v_pk_mul_f32 v[88:89], v[88:89], v[244:245]
	global_store_dwordx4 v[236:237], v[88:91], off offset:64
	s_waitcnt vmcnt(15)
	v_lshlrev_b32_e32 v244, 16, v176
	v_and_b32_e32 v245, 0xffff0000, v176
	v_lshlrev_b32_e32 v176, 16, v177
	v_and_b32_e32 v177, 0xffff0000, v177
	v_pk_mul_f32 v[86:87], v[86:87], v[176:177]
	v_pk_mul_f32 v[84:85], v[84:85], v[244:245]
	global_store_dwordx4 v[236:237], v[84:87], off offset:128
	s_waitcnt vmcnt(15)
	v_lshlrev_b32_e32 v244, 16, v178
	v_and_b32_e32 v245, 0xffff0000, v178
	v_lshlrev_b32_e32 v178, 16, v179
	v_and_b32_e32 v179, 0xffff0000, v179
	v_pk_mul_f32 v[82:83], v[82:83], v[178:179]
	v_pk_mul_f32 v[80:81], v[80:81], v[244:245]
	global_store_dwordx4 v[236:237], v[80:83], off offset:192
	s_waitcnt vmcnt(15)
	v_lshlrev_b32_e32 v244, 16, v180
	v_and_b32_e32 v245, 0xffff0000, v180
	v_lshlrev_b32_e32 v180, 16, v181
	v_and_b32_e32 v181, 0xffff0000, v181
	v_pk_mul_f32 v[78:79], v[78:79], v[180:181]
	v_pk_mul_f32 v[76:77], v[76:77], v[244:245]
	global_store_dwordx4 v[238:239], v[76:79], off
	s_waitcnt vmcnt(15)
	v_lshlrev_b32_e32 v244, 16, v182
	v_and_b32_e32 v245, 0xffff0000, v182
	v_lshlrev_b32_e32 v182, 16, v183
	v_and_b32_e32 v183, 0xffff0000, v183
	v_pk_mul_f32 v[74:75], v[74:75], v[182:183]
	v_pk_mul_f32 v[72:73], v[72:73], v[244:245]
	global_store_dwordx4 v[238:239], v[72:75], off offset:64
	s_waitcnt vmcnt(15)
	v_lshlrev_b32_e32 v244, 16, v226
	v_and_b32_e32 v245, 0xffff0000, v226
	v_lshlrev_b32_e32 v226, 16, v227
	v_and_b32_e32 v227, 0xffff0000, v227
	v_pk_mul_f32 v[70:71], v[70:71], v[226:227]
	v_pk_mul_f32 v[68:69], v[68:69], v[244:245]
	global_store_dwordx4 v[238:239], v[68:71], off offset:128
	s_waitcnt vmcnt(15)
	v_lshlrev_b32_e32 v244, 16, v228
	v_and_b32_e32 v245, 0xffff0000, v228
	v_lshlrev_b32_e32 v228, 16, v229
	v_and_b32_e32 v229, 0xffff0000, v229
	v_pk_mul_f32 v[66:67], v[66:67], v[228:229]
	v_pk_mul_f32 v[64:65], v[64:65], v[244:245]
	global_store_dwordx4 v[238:239], v[64:67], off offset:192
	s_setprio 0
	s_branch .LBB0_450
; DI unsigned pack2(float a, float b) { return (unsigned)f2bf(a) | ((unsigned)f2bf(b) << 16); }
; DI float bflo(unsigned w) { return __uint_as_float(w << 16); }
; DI float bfhi(unsigned w) { return __uint_as_float(w & 0xffff0000u); }
;   DI void operator()(f32x4 (&acc)[4][4], int m0w, int n0w, int fr, int fq) const {
;     ...
;         const size_t o = (size_t)(m0w + mi * 16 + fr) * D + n0w + ni * 16 + fq * 4;
;         const uint2 gw = *(const uint2*)(G + o);
;         f32x4 m;
;         m[0] = bflo(gw.x) * acc[mi][ni][0]; m[1] = bfhi(gw.x) * acc[mi][ni][1];
;         m[2] = bflo(gw.y) * acc[mi][ni][2]; m[3] = bfhi(gw.y) * acc[mi][ni][3];
;         if (b > 0) m += *(const f32x4*)(MACC + o);
;         if (b < 2) *(f32x4*)(MACC + o) = m;
;         else { uint2 w; w.x = pack2(m[0], m[1]); w.y = pack2(m[2], m[3]); *(uint2*)(MERGED + o) = w; }
.Lem_np:
	s_waitcnt vmcnt(15)
	v_lshlrev_b32_e32 v244, 16, v156
	v_and_b32_e32 v245, 0xffff0000, v156
	v_lshlrev_b32_e32 v156, 16, v157
	v_and_b32_e32 v157, 0xffff0000, v157
	v_pk_mul_f32 v[126:127], v[126:127], v[156:157]
	v_pk_mul_f32 v[124:125], v[124:125], v[244:245]
	v_lshl_add_u64 v[240:241], v[140:141], 0, s[2:3]
	v_cvt_pk_bf16_f32 v124, v124, v125
	v_cvt_pk_bf16_f32 v125, v126, v127
	global_store_dwordx2 v[240:241], v[124:125], off
	s_waitcnt vmcnt(15)
	v_lshlrev_b32_e32 v244, 16, v158
	v_and_b32_e32 v245, 0xffff0000, v158
	v_lshlrev_b32_e32 v158, 16, v159
	v_and_b32_e32 v159, 0xffff0000, v159
	v_pk_mul_f32 v[122:123], v[122:123], v[158:159]
	v_pk_mul_f32 v[120:121], v[120:121], v[244:245]
	v_cvt_pk_bf16_f32 v120, v120, v121
	v_cvt_pk_bf16_f32 v121, v122, v123
	global_store_dwordx2 v[240:241], v[120:121], off offset:32
	s_waitcnt vmcnt(15)
	v_lshlrev_b32_e32 v244, 16, v160
	v_and_b32_e32 v245, 0xffff0000, v160
	v_lshlrev_b32_e32 v160, 16, v161
	v_and_b32_e32 v161, 0xffff0000, v161
	v_pk_mul_f32 v[118:119], v[118:119], v[160:161]
	v_pk_mul_f32 v[116:117], v[116:117], v[244:245]
	v_cvt_pk_bf16_f32 v116, v116, v117
	v_cvt_pk_bf16_f32 v117, v118, v119
	global_store_dwordx2 v[240:241], v[116:117], off offset:64
	s_waitcnt vmcnt(15)
	v_lshlrev_b32_e32 v244, 16, v162
	v_and_b32_e32 v245, 0xffff0000, v162
	v_lshlrev_b32_e32 v162, 16, v163
	v_and_b32_e32 v163, 0xffff0000, v163
	v_pk_mul_f32 v[114:115], v[114:115], v[162:163]
	v_pk_mul_f32 v[112:113], v[112:113], v[244:245]
	v_cvt_pk_bf16_f32 v112, v112, v113
	v_cvt_pk_bf16_f32 v113, v114, v115
	global_store_dwordx2 v[240:241], v[112:113], off offset:96
	s_waitcnt vmcnt(15)
	v_lshlrev_b32_e32 v244, 16, v164
	v_and_b32_e32 v245, 0xffff0000, v164
	v_lshlrev_b32_e32 v164, 16, v165
	v_and_b32_e32 v165, 0xffff0000, v165
	v_pk_mul_f32 v[110:111], v[110:111], v[164:165]
	v_pk_mul_f32 v[108:109], v[108:109], v[244:245]
	v_lshl_add_u64 v[242:243], v[142:143], 0, s[2:3]
	v_cvt_pk_bf16_f32 v108, v108, v109
	v_cvt_pk_bf16_f32 v109, v110, v111
	global_store_dwordx2 v[242:243], v[108:109], off
	s_waitcnt vmcnt(15)
	v_lshlrev_b32_e32 v244, 16, v166
	v_and_b32_e32 v245, 0xffff0000, v166
	v_lshlrev_b32_e32 v166, 16, v167
	v_and_b32_e32 v167, 0xffff0000, v167
	v_pk_mul_f32 v[106:107], v[106:107], v[166:167]
	v_pk_mul_f32 v[104:105], v[104:105], v[244:245]
	v_cvt_pk_bf16_f32 v104, v104, v105
	v_cvt_pk_bf16_f32 v105, v106, v107
	global_store_dwordx2 v[242:243], v[104:105], off offset:32
	s_waitcnt vmcnt(15)
	v_lshlrev_b32_e32 v244, 16, v168
	v_and_b32_e32 v245, 0xffff0000, v168
	v_lshlrev_b32_e32 v168, 16, v169
	v_and_b32_e32 v169, 0xffff0000, v169
	v_pk_mul_f32 v[102:103], v[102:103], v[168:169]
	v_pk_mul_f32 v[100:101], v[100:101], v[244:245]
	v_cvt_pk_bf16_f32 v100, v100, v101
	v_cvt_pk_bf16_f32 v101, v102, v103
	global_store_dwordx2 v[242:243], v[100:101], off offset:64
	s_waitcnt vmcnt(15)
	v_lshlrev_b32_e32 v244, 16, v170
	v_and_b32_e32 v245, 0xffff0000, v170
	v_lshlrev_b32_e32 v170, 16, v171
	v_and_b32_e32 v171, 0xffff0000, v171
	v_pk_mul_f32 v[98:99], v[98:99], v[170:171]
	v_pk_mul_f32 v[96:97], v[96:97], v[244:245]
	v_cvt_pk_bf16_f32 v96, v96, v97
	v_cvt_pk_bf16_f32 v97, v98, v99
	global_store_dwordx2 v[242:243], v[96:97], off offset:96
	s_waitcnt vmcnt(15)
	v_lshlrev_b32_e32 v244, 16, v172
	v_and_b32_e32 v245, 0xffff0000, v172
	v_lshlrev_b32_e32 v172, 16, v173
	v_and_b32_e32 v173, 0xffff0000, v173
	v_pk_mul_f32 v[94:95], v[94:95], v[172:173]
	v_pk_mul_f32 v[92:93], v[92:93], v[244:245]
	v_lshl_add_u64 v[240:241], v[146:147], 0, s[2:3]
	v_cvt_pk_bf16_f32 v92, v92, v93
	v_cvt_pk_bf16_f32 v93, v94, v95
	global_store_dwordx2 v[240:241], v[92:93], off
	s_waitcnt vmcnt(15)
	v_lshlrev_b32_e32 v244, 16, v174
	v_and_b32_e32 v245, 0xffff0000, v174
	v_lshlrev_b32_e32 v174, 16, v175
	v_and_b32_e32 v175, 0xffff0000, v175
	v_pk_mul_f32 v[90:91], v[90:91], v[174:175]
	v_pk_mul_f32 v[88:89], v[88:89], v[244:245]
	v_cvt_pk_bf16_f32 v88, v88, v89
	v_cvt_pk_bf16_f32 v89, v90, v91
	global_store_dwordx2 v[240:241], v[88:89], off offset:32
	s_waitcnt vmcnt(15)
	v_lshlrev_b32_e32 v244, 16, v176
	v_and_b32_e32 v245, 0xffff0000, v176
	v_lshlrev_b32_e32 v176, 16, v177
	v_and_b32_e32 v177, 0xffff0000, v177
	v_pk_mul_f32 v[86:87], v[86:87], v[176:177]
	v_pk_mul_f32 v[84:85], v[84:85], v[244:245]
	v_cvt_pk_bf16_f32 v84, v84, v85
	v_cvt_pk_bf16_f32 v85, v86, v87
	global_store_dwordx2 v[240:241], v[84:85], off offset:64
	s_waitcnt vmcnt(15)
	v_lshlrev_b32_e32 v244, 16, v178
	v_and_b32_e32 v245, 0xffff0000, v178
	v_lshlrev_b32_e32 v178, 16, v179
	v_and_b32_e32 v179, 0xffff0000, v179
	v_pk_mul_f32 v[82:83], v[82:83], v[178:179]
	v_pk_mul_f32 v[80:81], v[80:81], v[244:245]
	v_cvt_pk_bf16_f32 v80, v80, v81
	v_cvt_pk_bf16_f32 v81, v82, v83
	global_store_dwordx2 v[240:241], v[80:81], off offset:96
	s_waitcnt vmcnt(15)
	v_lshlrev_b32_e32 v244, 16, v180
	v_and_b32_e32 v245, 0xffff0000, v180
	v_lshlrev_b32_e32 v180, 16, v181
	v_and_b32_e32 v181, 0xffff0000, v181
	v_pk_mul_f32 v[78:79], v[78:79], v[180:181]
	v_pk_mul_f32 v[76:77], v[76:77], v[244:245]
	v_lshl_add_u64 v[242:243], v[148:149], 0, s[2:3]
	v_cvt_pk_bf16_f32 v76, v76, v77
	v_cvt_pk_bf16_f32 v77, v78, v79
	global_store_dwordx2 v[242:243], v[76:77], off
	s_waitcnt vmcnt(15)
	v_lshlrev_b32_e32 v244, 16, v182
	v_and_b32_e32 v245, 0xffff0000, v182
	v_lshlrev_b32_e32 v182, 16, v183
	v_and_b32_e32 v183, 0xffff0000, v183
	v_pk_mul_f32 v[74:75], v[74:75], v[182:183]
	v_pk_mul_f32 v[72:73], v[72:73], v[244:245]
	v_cvt_pk_bf16_f32 v72, v72, v73
	v_cvt_pk_bf16_f32 v73, v74, v75
	global_store_dwordx2 v[242:243], v[72:73], off offset:32
	s_waitcnt vmcnt(15)
	v_lshlrev_b32_e32 v244, 16, v226
	v_and_b32_e32 v245, 0xffff0000, v226
	v_lshlrev_b32_e32 v226, 16, v227
	v_and_b32_e32 v227, 0xffff0000, v227
	v_pk_mul_f32 v[70:71], v[70:71], v[226:227]
	v_pk_mul_f32 v[68:69], v[68:69], v[244:245]
	v_cvt_pk_bf16_f32 v68, v68, v69
	v_cvt_pk_bf16_f32 v69, v70, v71
	global_store_dwordx2 v[242:243], v[68:69], off offset:64
	s_waitcnt vmcnt(15)
	v_lshlrev_b32_e32 v244, 16, v228
	v_and_b32_e32 v245, 0xffff0000, v228
	v_lshlrev_b32_e32 v228, 16, v229
	v_and_b32_e32 v229, 0xffff0000, v229
	v_pk_mul_f32 v[66:67], v[66:67], v[228:229]
	v_pk_mul_f32 v[64:65], v[64:65], v[244:245]
	v_cvt_pk_bf16_f32 v64, v64, v65
	v_cvt_pk_bf16_f32 v65, v66, v67
	global_store_dwordx2 v[242:243], v[64:65], off offset:96
	s_setprio 0
	s_branch .LBB0_450
